# GEMM K-loop: the four k=1 A-fragment LDS reads of each 8-read section issued inside the following MFMA block's shadow (stage overwritten two slots later), pre-barrier wait lowered to lgkmcnt(4)
# speedup vs baseline: 1.0043x; 1.0043x over previous
; #define LDA(dst, b, h) for (int m = 0; m < 4; ++m) for (int k = 0; k < 2; ++k) \
;     dst[m][k] = *reinterpret_cast<const bf16x8*>(SA(b, h) + lds_byte(wr * 64 + m * 16 + fr, k * 32 + fq * 8))
; #define LDB(dst, b, h) for (int n = 0; n < 2; ++n) for (int k = 0; k < 2; ++k) \
;     dst[n][k] = *reinterpret_cast<const bf16x8*>(SB(b, h) + lds_byte(wc * 32 + n * 16 + fr, k * 32 + fq * 8))
; #define MMA(ai, bj, At_, Bt_) do { __builtin_amdgcn_s_setprio(1); \
;     for (int m = 0; m < 4; ++m) for (int n = 0; n < 2; ++n) for (int k = 0; k < 2; ++k) \
;       acc[ai][bj][m][n] = __builtin_amdgcn_mfma_f32_16x16x32_bf16(Bt_[n][k], At_[m][k], acc[ai][bj][m][n], 0, 0, 0); \
;     __builtin_amdgcn_s_setprio(0); } while (0)
; #define WAIT_L(n) asm volatile("s_waitcnt lgkmcnt(" #n ")" ::: "memory")
; #define BAR __builtin_amdgcn_s_barrier()
; #define SCHED __builtin_amdgcn_sched_barrier(0)
; #define STG(P, PTR, LD, O0) do { const bf16_t* _g = (PTR); \
;     __builtin_amdgcn_global_load_lds((const unsigned*)(_g + O0), (lds_u32*)((P) + swave * 1024), 16, 0, 0); \
;     __builtin_amdgcn_global_load_lds((const unsigned*)(_g + (size_t)64 * (LD) + O0), (lds_u32*)((P) + swave * 1024 + 8192), 16, 0, 0); } while (0)
; #define LDA(dst, b, h) for (int m = 0; m < 4; ++m) for (int k = 0; k < 2; ++k) \
;     dst[m][k] = *reinterpret_cast<const bf16x8*>(SA(b, h) + lds_byte(wr * 64 + m * 16 + fr, k * 32 + fq * 8))
; #define LDB(dst, b, h) for (int n = 0; n < 2; ++n) for (int k = 0; k < 2; ++k) \
;     dst[n][k] = *reinterpret_cast<const bf16x8*>(SB(b, h) + lds_byte(wc * 32 + n * 16 + fr, k * 32 + fq * 8))
; __device__ __forceinline__ void gemm_stream(int swave, const GemmJob& J, char* shm, int vb, int G) {
;     ...
;       const bool last = (t == nt - 2);
;       const bf16_t* xA = last ? nA : cA; const bf16_t* xA1 = last ? nA1 : cA1; const int k2 = last ? 0 : t + 2;
;       const bf16_t* b2 = last ? nB : cB + (size_t)(t + 2) * 64; const bf16_t* b3 = b2 + 64;
;       LDB(B0, 0, 0); SCHED; LDA(At, 0, 0); STGA(SA(1, 1), cA, cA1, t + 1, 1);
;       WAIT_L(8); BAR; WAIT_L(0); MMA(0, 0, At, B0); BAR; SCHED;
;       LDB(B1, 0, 1); STG(SB(0, 0), b2, ldb, offB0);
;       BAR; WAIT_L(0); MMA(0, 1, At, B1); BAR;
;       LDA(At, 0, 1); STGA(SA(0, 0), xA, xA1, k2, 0);
;       BAR; WAIT_L(0); MMA(1, 0, At, B0); BAR; SCHED;
;       STG(SB(0, 1), b2 + hB, ldb, offB0);
.LBB0_729:
	ds_read_b128 v[164:167], v139
	ds_read_b128 v[168:171], v139 offset:1024
	ds_read_b128 v[172:175], v139 offset:2048
	ds_read_b128 v[176:179], v139 offset:3072
	s_cmp_eq_u32 s49, s29
	s_cselect_b64 s[68:69], -1, 0
	s_and_b64 s[64:65], s[68:69], exec
	s_cselect_b32 s52, s10, s8
	s_cselect_b32 s64, s11, s9
	s_add_i32 s33, s2, 2
	s_and_b64 s[68:69], s[68:69], exec
	s_cselect_b32 s71, s15, s21
	s_cselect_b32 s70, s14, s20
	s_cselect_b32 s68, 0, s33
	s_cselect_b32 s65, s12, s16
	s_cselect_b32 s66, s13, s17
	s_or_b32 s2, s2, 1
	s_cmp_lt_u32 s2, s36
	s_cselect_b64 vcc, -1, 0
	s_and_b64 s[2:3], vcc, exec
	s_cselect_b32 s3, 0, s36
	s_cselect_b32 s2, s38, s37
	s_not_b32 s3, s3
	s_add_i32 s94, s3, s29
	s_and_b64 s[72:73], vcc, exec
	s_cselect_b32 s3, s9, s17
	s_cselect_b32 s69, s8, s16
	s_lshl_b64 s[72:73], s[94:95], 7
	s_add_u32 s69, s69, s72
	s_addc_u32 s74, s3, s73
	s_mov_b32 s3, s95
	s_lshl_b64 s[72:73], s[2:3], 8
	s_add_u32 s72, s69, s72
	v_cndmask_b32_e32 v2, v138, v0, vcc
	s_addc_u32 s73, s74, s73
	s_add_i32 m0, s42, 0xc000
	s_lshl_b64 s[2:3], s[2:3], 7
	v_lshlrev_b64 v[212:213], 1, v[2:3]
	s_add_u32 s2, s72, s2
	v_lshl_add_u64 v[214:215], s[72:73], 0, v[212:213]
	s_addc_u32 s3, s73, s3
	ds_read_b128 v[180:183], v144
	ds_read_b128 v[188:191], v145
	ds_read_b128 v[196:199], v159
	ds_read_b128 v[204:207], v160
	global_load_lds_dwordx4 v[214:215], off
	v_lshl_add_u64 v[212:213], s[2:3], 0, v[212:213]
	s_add_i32 m0, s42, 0xe000
	s_nop 0
	global_load_lds_dwordx4 v[212:213], off
	s_waitcnt lgkmcnt(4)
	s_barrier
	s_waitcnt lgkmcnt(0)
	v_mfma_f32_16x16x32_bf16 v[128:131], v[164:167], v[180:183], v[128:131]
	ds_read_b128 v[184:187], v144 offset:1024
	v_mfma_f32_16x16x32_bf16 v[124:127], v[172:175], v[180:183], v[124:127]
	ds_read_b128 v[192:195], v145 offset:1024
	v_mfma_f32_16x16x32_bf16 v[120:123], v[164:167], v[188:191], v[120:123]
	ds_read_b128 v[200:203], v159 offset:1024
	v_mfma_f32_16x16x32_bf16 v[116:119], v[172:175], v[188:191], v[116:119]
	ds_read_b128 v[208:211], v160 offset:1024
	v_mfma_f32_16x16x32_bf16 v[104:107], v[164:167], v[196:199], v[104:107]
	v_mfma_f32_16x16x32_bf16 v[100:103], v[172:175], v[196:199], v[100:103]
	v_mfma_f32_16x16x32_bf16 v[88:91], v[164:167], v[204:207], v[88:91]
	v_mfma_f32_16x16x32_bf16 v[84:87], v[172:175], v[204:207], v[84:87]
	s_waitcnt lgkmcnt(0)
	v_mfma_f32_16x16x32_bf16 v[128:131], v[168:171], v[184:187], v[128:131]
	v_mfma_f32_16x16x32_bf16 v[124:127], v[176:179], v[184:187], v[124:127]
	v_mfma_f32_16x16x32_bf16 v[120:123], v[168:171], v[192:195], v[120:123]
	v_mfma_f32_16x16x32_bf16 v[116:119], v[176:179], v[192:195], v[116:119]
	v_mfma_f32_16x16x32_bf16 v[104:107], v[168:171], v[200:203], v[104:107]
	v_mfma_f32_16x16x32_bf16 v[100:103], v[176:179], v[200:203], v[100:103]
	v_mfma_f32_16x16x32_bf16 v[88:91], v[168:171], v[208:211], v[88:91]
	v_mfma_f32_16x16x32_bf16 v[84:87], v[176:179], v[208:211], v[84:87]
	s_barrier
	s_add_u32 s2, s70, s0
	s_mov_b32 m0, s43
	v_lshl_add_u64 v[228:229], s[70:71], 0, v[136:137]
	s_addc_u32 s3, s71, s1
	ds_read_b128 v[212:215], v161
	ds_read_b128 v[216:219], v161 offset:1024
	ds_read_b128 v[220:223], v161 offset:2048
	ds_read_b128 v[224:227], v161 offset:3072
	global_load_lds_dwordx4 v[228:229], off
	v_lshl_add_u64 v[230:231], s[2:3], 0, v[136:137]
	s_mov_b32 m0, s44
	s_nop 0
	global_load_lds_dwordx4 v[230:231], off
	s_barrier
	s_waitcnt lgkmcnt(0)
	v_mfma_f32_16x16x32_bf16 v[112:115], v[212:215], v[180:183], v[112:115]
	v_mfma_f32_16x16x32_bf16 v[108:111], v[220:223], v[180:183], v[108:111]
	s_cmp_lt_u32 s68, s36
	s_cselect_b64 vcc, -1, 0
	v_mfma_f32_16x16x32_bf16 v[96:99], v[212:215], v[188:191], v[96:99]
	s_and_b64 s[70:71], vcc, exec
	s_cselect_b32 s70, s38, s37
	v_mfma_f32_16x16x32_bf16 v[92:95], v[220:223], v[188:191], v[92:95]
	s_sub_i32 s69, s68, s36
	s_min_u32 s94, s68, s69
	v_mfma_f32_16x16x32_bf16 v[80:83], v[212:215], v[196:199], v[80:83]
	s_and_b64 s[72:73], vcc, exec
	s_cselect_b32 s69, s64, s66
	v_mfma_f32_16x16x32_bf16 v[76:79], v[220:223], v[196:199], v[76:79]
	s_cselect_b32 s71, s52, s65
	s_lshl_b64 s[72:73], s[94:95], 7
	v_mfma_f32_16x16x32_bf16 v[72:75], v[212:215], v[204:207], v[72:75]
	v_cndmask_b32_e32 v2, v138, v0, vcc
	s_add_u32 s72, s71, s72
	v_mfma_f32_16x16x32_bf16 v[68:71], v[220:223], v[204:207], v[68:71]
	s_mov_b32 s71, s95
	v_mfma_f32_16x16x32_bf16 v[112:115], v[216:219], v[184:187], v[112:115]
	s_addc_u32 s73, s69, s73
	v_mfma_f32_16x16x32_bf16 v[108:111], v[224:227], v[184:187], v[108:111]
	v_lshlrev_b64 v[232:233], 1, v[2:3]
	v_mfma_f32_16x16x32_bf16 v[96:99], v[216:219], v[192:195], v[96:99]
	s_lshl_b64 s[70:71], s[70:71], 7
	v_mfma_f32_16x16x32_bf16 v[92:95], v[224:227], v[192:195], v[92:95]
	v_lshl_add_u64 v[234:235], s[72:73], 0, v[232:233]
	v_mfma_f32_16x16x32_bf16 v[80:83], v[216:219], v[200:203], v[80:83]
	s_add_u32 s72, s72, s70
	v_mfma_f32_16x16x32_bf16 v[76:79], v[224:227], v[200:203], v[76:79]
	s_mov_b32 m0, s42
	v_mfma_f32_16x16x32_bf16 v[72:75], v[216:219], v[208:211], v[72:75]
	s_addc_u32 s73, s73, s71
	v_mfma_f32_16x16x32_bf16 v[68:71], v[224:227], v[208:211], v[68:71]
	s_barrier
	ds_read_b128 v[180:183], v144 offset:16384
	ds_read_b128 v[188:191], v145 offset:16384
	ds_read_b128 v[196:199], v159 offset:16384
	ds_read_b128 v[204:207], v160 offset:16384
	global_load_lds_dwordx4 v[234:235], off
	v_lshl_add_u64 v[234:235], s[72:73], 0, v[232:233]
	s_mov_b32 m0, s39
	s_nop 0
	global_load_lds_dwordx4 v[234:235], off
	s_barrier
; #define LDA(dst, b, h) for (int m = 0; m < 4; ++m) for (int k = 0; k < 2; ++k) \
;     dst[m][k] = *reinterpret_cast<const bf16x8*>(SA(b, h) + lds_byte(wr * 64 + m * 16 + fr, k * 32 + fq * 8))
; #define LDB(dst, b, h) for (int n = 0; n < 2; ++n) for (int k = 0; k < 2; ++k) \
;     dst[n][k] = *reinterpret_cast<const bf16x8*>(SB(b, h) + lds_byte(wc * 32 + n * 16 + fr, k * 32 + fq * 8))
; #define MMA(ai, bj, At_, Bt_) do { __builtin_amdgcn_s_setprio(1); \
;     for (int m = 0; m < 4; ++m) for (int n = 0; n < 2; ++n) for (int k = 0; k < 2; ++k) \
;       acc[ai][bj][m][n] = __builtin_amdgcn_mfma_f32_16x16x32_bf16(Bt_[n][k], At_[m][k], acc[ai][bj][m][n], 0, 0, 0); \
;     __builtin_amdgcn_s_setprio(0); } while (0)
; #define WAIT_V(n) asm volatile("s_waitcnt vmcnt(" #n ")" ::: "memory")
; #define WAIT_L(n) asm volatile("s_waitcnt lgkmcnt(" #n ")" ::: "memory")
; #define BAR __builtin_amdgcn_s_barrier()
; #define SCHED __builtin_amdgcn_sched_barrier(0)
; #define STG(P, PTR, LD, O0) do { const bf16_t* _g = (PTR); \
;     __builtin_amdgcn_global_load_lds((const unsigned*)(_g + O0), (lds_u32*)((P) + swave * 1024), 16, 0, 0); \
;     __builtin_amdgcn_global_load_lds((const unsigned*)(_g + (size_t)64 * (LD) + O0), (lds_u32*)((P) + swave * 1024 + 8192), 16, 0, 0); } while (0)
; #define LDA(dst, b, h) for (int m = 0; m < 4; ++m) for (int k = 0; k < 2; ++k) \
;     dst[m][k] = *reinterpret_cast<const bf16x8*>(SA(b, h) + lds_byte(wr * 64 + m * 16 + fr, k * 32 + fq * 8))
; #define LDB(dst, b, h) for (int n = 0; n < 2; ++n) for (int k = 0; k < 2; ++k) \
;     dst[n][k] = *reinterpret_cast<const bf16x8*>(SB(b, h) + lds_byte(wc * 32 + n * 16 + fr, k * 32 + fq * 8))
; #define WAIT_V(n) asm volatile("s_waitcnt vmcnt(" #n ")" ::: "memory")
; #define WAIT_L(n) asm volatile("s_waitcnt lgkmcnt(" #n ")" ::: "memory")
; #define BAR __builtin_amdgcn_s_barrier()
; #define SCHED __builtin_amdgcn_sched_barrier(0)
; __device__ __forceinline__ void gemm_stream(int swave, const GemmJob& J, char* shm, int vb, int G) {
;     ...
;       BAR; WAIT_L(0); MMA(1, 0, At, B0); BAR; SCHED;
;       STG(SB(0, 1), b2 + hB, ldb, offB0);
;       WAIT_V(6); BAR; MMA(1, 1, At, B1); BAR;
;       LDB(B0, 1, 0); SCHED; LDA(At, 1, 0); STGA(SA(0, 1), xA, xA1, k2, 1);
;       WAIT_L(8); BAR; WAIT_L(0); MMA(0, 0, At, B0); BAR; SCHED;
;       LDB(B1, 1, 1); STG(SB(1, 0), b3, ldb, offB0);
	s_waitcnt lgkmcnt(0)
	v_mfma_f32_16x16x32_bf16 v[64:67], v[164:167], v[180:183], v[64:67]
	ds_read_b128 v[184:187], v144 offset:17408
	v_mfma_f32_16x16x32_bf16 v[60:63], v[172:175], v[180:183], v[60:63]
	ds_read_b128 v[192:195], v145 offset:17408
	v_mfma_f32_16x16x32_bf16 v[56:59], v[164:167], v[188:191], v[56:59]
	ds_read_b128 v[200:203], v159 offset:17408
	v_mfma_f32_16x16x32_bf16 v[52:55], v[172:175], v[188:191], v[52:55]
	ds_read_b128 v[208:211], v160 offset:17408
	v_mfma_f32_16x16x32_bf16 v[40:43], v[164:167], v[196:199], v[40:43]
	v_mfma_f32_16x16x32_bf16 v[36:39], v[172:175], v[196:199], v[36:39]
	v_mfma_f32_16x16x32_bf16 v[24:27], v[164:167], v[204:207], v[24:27]
	v_mfma_f32_16x16x32_bf16 v[20:23], v[172:175], v[204:207], v[20:23]
	s_waitcnt lgkmcnt(0)
	v_mfma_f32_16x16x32_bf16 v[64:67], v[168:171], v[184:187], v[64:67]
	v_mfma_f32_16x16x32_bf16 v[60:63], v[176:179], v[184:187], v[60:63]
	v_mfma_f32_16x16x32_bf16 v[56:59], v[168:171], v[192:195], v[56:59]
	v_mfma_f32_16x16x32_bf16 v[52:55], v[176:179], v[192:195], v[52:55]
	v_mfma_f32_16x16x32_bf16 v[40:43], v[168:171], v[200:203], v[40:43]
	v_mfma_f32_16x16x32_bf16 v[36:39], v[176:179], v[200:203], v[36:39]
	v_mfma_f32_16x16x32_bf16 v[24:27], v[168:171], v[208:211], v[24:27]
	v_mfma_f32_16x16x32_bf16 v[20:23], v[176:179], v[208:211], v[20:23]
	s_barrier
	s_add_u32 s2, s2, s0
	s_addc_u32 s3, s3, s1
	v_lshl_add_u64 v[234:235], s[2:3], 0, v[136:137]
	s_add_u32 s2, s2, s0
	s_mov_b32 m0, s45
	s_addc_u32 s3, s3, s1
	global_load_lds_dwordx4 v[234:235], off
	v_lshl_add_u64 v[236:237], s[2:3], 0, v[136:137]
	s_mov_b32 m0, s46
	s_nop 0
	global_load_lds_dwordx4 v[236:237], off
	s_waitcnt vmcnt(6)
	s_barrier
	v_mfma_f32_16x16x32_bf16 v[48:51], v[212:215], v[180:183], v[48:51]
	v_mfma_f32_16x16x32_bf16 v[44:47], v[220:223], v[180:183], v[44:47]
	v_mfma_f32_16x16x32_bf16 v[32:35], v[212:215], v[188:191], v[32:35]
	v_mfma_f32_16x16x32_bf16 v[28:31], v[220:223], v[188:191], v[28:31]
	v_mfma_f32_16x16x32_bf16 v[16:19], v[212:215], v[196:199], v[16:19]
	v_mfma_f32_16x16x32_bf16 v[12:15], v[220:223], v[196:199], v[12:15]
	v_mfma_f32_16x16x32_bf16 v[8:11], v[212:215], v[204:207], v[8:11]
	v_mfma_f32_16x16x32_bf16 v[4:7], v[220:223], v[204:207], v[4:7]
	v_mfma_f32_16x16x32_bf16 v[48:51], v[216:219], v[184:187], v[48:51]
	v_mfma_f32_16x16x32_bf16 v[44:47], v[224:227], v[184:187], v[44:47]
	v_mfma_f32_16x16x32_bf16 v[32:35], v[216:219], v[192:195], v[32:35]
	v_mfma_f32_16x16x32_bf16 v[28:31], v[224:227], v[192:195], v[28:31]
	v_mfma_f32_16x16x32_bf16 v[16:19], v[216:219], v[200:203], v[16:19]
	v_mfma_f32_16x16x32_bf16 v[12:15], v[224:227], v[200:203], v[12:15]
	v_mfma_f32_16x16x32_bf16 v[8:11], v[216:219], v[208:211], v[8:11]
	v_mfma_f32_16x16x32_bf16 v[4:7], v[224:227], v[208:211], v[4:7]
	s_barrier
	ds_read_b128 v[164:167], v162
	ds_read_b128 v[168:171], v162 offset:1024
	ds_read_b128 v[172:175], v162 offset:2048
	ds_read_b128 v[176:179], v162 offset:3072
	s_add_u32 s2, s72, s70
	s_addc_u32 s3, s73, s71
	v_lshl_add_u64 v[212:213], s[2:3], 0, v[232:233]
	s_add_u32 s2, s2, s70
	s_mov_b32 m0, s47
	s_addc_u32 s3, s3, s71
	ds_read_b128 v[180:183], v144 offset:32768
	ds_read_b128 v[188:191], v145 offset:32768
	ds_read_b128 v[196:199], v159 offset:32768
	ds_read_b128 v[204:207], v160 offset:32768
	global_load_lds_dwordx4 v[212:213], off
	v_lshl_add_u64 v[212:213], s[2:3], 0, v[232:233]
	s_mov_b32 m0, s48
	s_nop 0
	global_load_lds_dwordx4 v[212:213], off
	s_waitcnt lgkmcnt(4)
	s_barrier
	s_waitcnt lgkmcnt(0)
	v_mfma_f32_16x16x32_bf16 v[128:131], v[164:167], v[180:183], v[128:131]
	ds_read_b128 v[184:187], v144 offset:33792
	v_mfma_f32_16x16x32_bf16 v[124:127], v[172:175], v[180:183], v[124:127]
	ds_read_b128 v[192:195], v145 offset:33792
	v_mfma_f32_16x16x32_bf16 v[120:123], v[164:167], v[188:191], v[120:123]
	ds_read_b128 v[200:203], v159 offset:33792
	v_mfma_f32_16x16x32_bf16 v[116:119], v[172:175], v[188:191], v[116:119]
	ds_read_b128 v[208:211], v160 offset:33792
	v_mfma_f32_16x16x32_bf16 v[104:107], v[164:167], v[196:199], v[104:107]
	v_mfma_f32_16x16x32_bf16 v[100:103], v[172:175], v[196:199], v[100:103]
	v_mfma_f32_16x16x32_bf16 v[88:91], v[164:167], v[204:207], v[88:91]
	v_mfma_f32_16x16x32_bf16 v[84:87], v[172:175], v[204:207], v[84:87]
	s_waitcnt lgkmcnt(0)
	v_mfma_f32_16x16x32_bf16 v[128:131], v[168:171], v[184:187], v[128:131]
	v_mfma_f32_16x16x32_bf16 v[124:127], v[176:179], v[184:187], v[124:127]
	v_mfma_f32_16x16x32_bf16 v[120:123], v[168:171], v[192:195], v[120:123]
	v_mfma_f32_16x16x32_bf16 v[116:119], v[176:179], v[192:195], v[116:119]
	v_mfma_f32_16x16x32_bf16 v[104:107], v[168:171], v[200:203], v[104:107]
	v_mfma_f32_16x16x32_bf16 v[100:103], v[176:179], v[200:203], v[100:103]
	v_mfma_f32_16x16x32_bf16 v[88:91], v[168:171], v[208:211], v[88:91]
	v_mfma_f32_16x16x32_bf16 v[84:87], v[176:179], v[208:211], v[84:87]
	s_barrier
	v_lshl_add_u64 v[228:229], v[228:229], 0, s[22:23]
	s_add_i32 m0, s42, 0x18000
	ds_read_b128 v[212:215], v163
	ds_read_b128 v[216:219], v163 offset:1024
	ds_read_b128 v[220:223], v163 offset:2048
	ds_read_b128 v[224:227], v163 offset:3072
	global_load_lds_dwordx4 v[228:229], off
	v_lshl_add_u64 v[228:229], v[230:231], 0, s[22:23]
	s_add_i32 m0, s42, 0x1a000
	s_nop 0
	global_load_lds_dwordx4 v[228:229], off
	s_barrier
; #define LDA(dst, b, h) for (int m = 0; m < 4; ++m) for (int k = 0; k < 2; ++k) \
;     dst[m][k] = *reinterpret_cast<const bf16x8*>(SA(b, h) + lds_byte(wr * 64 + m * 16 + fr, k * 32 + fq * 8))
; #define MMA(ai, bj, At_, Bt_) do { __builtin_amdgcn_s_setprio(1); \
;     for (int m = 0; m < 4; ++m) for (int n = 0; n < 2; ++n) for (int k = 0; k < 2; ++k) \
;       acc[ai][bj][m][n] = __builtin_amdgcn_mfma_f32_16x16x32_bf16(Bt_[n][k], At_[m][k], acc[ai][bj][m][n], 0, 0, 0); \
;     __builtin_amdgcn_s_setprio(0); } while (0)
; #define WAIT_V(n) asm volatile("s_waitcnt vmcnt(" #n ")" ::: "memory")
; #define WAIT_L(n) asm volatile("s_waitcnt lgkmcnt(" #n ")" ::: "memory")
; #define BAR __builtin_amdgcn_s_barrier()
; #define SCHED __builtin_amdgcn_sched_barrier(0)
; #define STG(P, PTR, LD, O0) do { const bf16_t* _g = (PTR); \
;     __builtin_amdgcn_global_load_lds((const unsigned*)(_g + O0), (lds_u32*)((P) + swave * 1024), 16, 0, 0); \
;     __builtin_amdgcn_global_load_lds((const unsigned*)(_g + (size_t)64 * (LD) + O0), (lds_u32*)((P) + swave * 1024 + 8192), 16, 0, 0); } while (0)
; #define LDA(dst, b, h) for (int m = 0; m < 4; ++m) for (int k = 0; k < 2; ++k) \
;     dst[m][k] = *reinterpret_cast<const bf16x8*>(SA(b, h) + lds_byte(wr * 64 + m * 16 + fr, k * 32 + fq * 8))
; #define MMA(ai, bj, At_, Bt_) do { __builtin_amdgcn_s_setprio(1); \
;     for (int m = 0; m < 4; ++m) for (int n = 0; n < 2; ++n) for (int k = 0; k < 2; ++k) \
;       acc[ai][bj][m][n] = __builtin_amdgcn_mfma_f32_16x16x32_bf16(Bt_[n][k], At_[m][k], acc[ai][bj][m][n], 0, 0, 0); \
;     __builtin_amdgcn_s_setprio(0); } while (0)
; #define WAIT_V(n) asm volatile("s_waitcnt vmcnt(" #n ")" ::: "memory")
; #define WAIT_L(n) asm volatile("s_waitcnt lgkmcnt(" #n ")" ::: "memory")
; #define BAR __builtin_amdgcn_s_barrier()
; #define SCHED __builtin_amdgcn_sched_barrier(0)
; __device__ __forceinline__ void gemm_stream(int swave, const GemmJob& J, char* shm, int vb, int G) {
;     ...
;       BAR; WAIT_L(0); MMA(0, 1, At, B1); BAR;
;       LDA(At, 1, 1); STGA(SA(1, 0), xA, xA1, k2 + 1, 0);
;       BAR; WAIT_L(0); MMA(1, 0, At, B0); BAR; SCHED;
;       STG(SB(1, 1), b3 + hB, ldb, offB0);
;       WAIT_V(6); BAR; MMA(1, 1, At, B1); BAR;
	s_waitcnt lgkmcnt(0)
	v_mfma_f32_16x16x32_bf16 v[112:115], v[212:215], v[180:183], v[112:115]
	v_mfma_f32_16x16x32_bf16 v[108:111], v[220:223], v[180:183], v[108:111]
	s_or_b32 s68, s68, 1
	s_cmp_lt_u32 s68, s36
	v_mfma_f32_16x16x32_bf16 v[96:99], v[212:215], v[188:191], v[96:99]
	s_cselect_b64 vcc, -1, 0
	s_and_b64 s[2:3], vcc, exec
	v_mfma_f32_16x16x32_bf16 v[92:95], v[220:223], v[188:191], v[92:95]
	s_cselect_b32 s69, s38, s37
	s_sub_i32 s2, s68, s36
	v_mfma_f32_16x16x32_bf16 v[80:83], v[212:215], v[196:199], v[80:83]
	s_min_u32 s94, s68, s2
	s_and_b64 s[2:3], vcc, exec
	v_mfma_f32_16x16x32_bf16 v[76:79], v[220:223], v[196:199], v[76:79]
	s_cselect_b32 s64, s64, s66
	s_cselect_b32 s52, s52, s65
	v_mfma_f32_16x16x32_bf16 v[72:75], v[212:215], v[204:207], v[72:75]
	s_lshl_b64 s[2:3], s[94:95], 7
	v_cndmask_b32_e32 v2, v138, v0, vcc
	v_mfma_f32_16x16x32_bf16 v[68:71], v[220:223], v[204:207], v[68:71]
	s_add_u32 s2, s52, s2
	v_mfma_f32_16x16x32_bf16 v[112:115], v[216:219], v[184:187], v[112:115]
	s_addc_u32 s3, s64, s3
	v_mfma_f32_16x16x32_bf16 v[108:111], v[224:227], v[184:187], v[108:111]
	v_lshlrev_b64 v[228:229], 1, v[2:3]
	v_mfma_f32_16x16x32_bf16 v[96:99], v[216:219], v[192:195], v[96:99]
	s_lshl_b32 s52, s69, 7
	v_mfma_f32_16x16x32_bf16 v[92:95], v[224:227], v[192:195], v[92:95]
	v_lshl_add_u64 v[230:231], s[2:3], 0, v[228:229]
	v_mfma_f32_16x16x32_bf16 v[80:83], v[216:219], v[200:203], v[80:83]
	s_add_u32 s2, s2, s52
	v_mfma_f32_16x16x32_bf16 v[76:79], v[224:227], v[200:203], v[76:79]
	s_mov_b32 m0, s54
	v_mfma_f32_16x16x32_bf16 v[72:75], v[216:219], v[208:211], v[72:75]
	s_addc_u32 s3, s3, 0
	v_mfma_f32_16x16x32_bf16 v[68:71], v[224:227], v[208:211], v[68:71]
	s_barrier
	ds_read_b128 v[180:183], v144 offset:49152
	ds_read_b128 v[188:191], v145 offset:49152
	ds_read_b128 v[196:199], v159 offset:49152
	ds_read_b128 v[204:207], v160 offset:49152
	global_load_lds_dwordx4 v[230:231], off
	v_lshl_add_u64 v[228:229], s[2:3], 0, v[228:229]
	s_mov_b32 m0, s55
	s_nop 0
	global_load_lds_dwordx4 v[228:229], off
	s_barrier
	s_waitcnt lgkmcnt(0)
	v_mfma_f32_16x16x32_bf16 v[64:67], v[164:167], v[180:183], v[64:67]
	ds_read_b128 v[184:187], v144 offset:50176
	v_mfma_f32_16x16x32_bf16 v[60:63], v[172:175], v[180:183], v[60:63]
	ds_read_b128 v[192:195], v145 offset:50176
	v_mfma_f32_16x16x32_bf16 v[56:59], v[164:167], v[188:191], v[56:59]
	ds_read_b128 v[200:203], v159 offset:50176
	v_mfma_f32_16x16x32_bf16 v[52:55], v[172:175], v[188:191], v[52:55]
	ds_read_b128 v[208:211], v160 offset:50176
	v_mfma_f32_16x16x32_bf16 v[40:43], v[164:167], v[196:199], v[40:43]
	v_mfma_f32_16x16x32_bf16 v[36:39], v[172:175], v[196:199], v[36:39]
	v_mfma_f32_16x16x32_bf16 v[24:27], v[164:167], v[204:207], v[24:27]
	v_mfma_f32_16x16x32_bf16 v[20:23], v[172:175], v[204:207], v[20:23]
	s_waitcnt lgkmcnt(0)
	v_mfma_f32_16x16x32_bf16 v[64:67], v[168:171], v[184:187], v[64:67]
	v_mfma_f32_16x16x32_bf16 v[60:63], v[176:179], v[184:187], v[60:63]
	v_mfma_f32_16x16x32_bf16 v[56:59], v[168:171], v[192:195], v[56:59]
	v_mfma_f32_16x16x32_bf16 v[52:55], v[176:179], v[192:195], v[52:55]
	v_mfma_f32_16x16x32_bf16 v[40:43], v[168:171], v[200:203], v[40:43]
	v_mfma_f32_16x16x32_bf16 v[36:39], v[176:179], v[200:203], v[36:39]
	v_mfma_f32_16x16x32_bf16 v[24:27], v[168:171], v[208:211], v[24:27]
	v_mfma_f32_16x16x32_bf16 v[20:23], v[176:179], v[208:211], v[20:23]
	s_barrier
	v_lshl_add_u64 v[164:165], v[234:235], 0, s[22:23]
	s_add_i32 m0, s42, 0x1c000
	s_nop 0
	global_load_lds_dwordx4 v[164:165], off
	v_lshl_add_u64 v[164:165], v[236:237], 0, s[22:23]
	s_add_i32 m0, s42, 0x1e000
	s_nop 0
	global_load_lds_dwordx4 v[164:165], off
	s_waitcnt vmcnt(6)
	s_barrier
	v_mfma_f32_16x16x32_bf16 v[48:51], v[212:215], v[180:183], v[48:51]
	v_mfma_f32_16x16x32_bf16 v[44:47], v[220:223], v[180:183], v[44:47]
	s_add_i32 s29, s29, 2
	v_mfma_f32_16x16x32_bf16 v[32:35], v[212:215], v[188:191], v[32:35]
	s_add_u32 s20, s20, 0x100
	v_mfma_f32_16x16x32_bf16 v[28:31], v[220:223], v[188:191], v[28:31]
	s_addc_u32 s21, s21, 0
	v_mfma_f32_16x16x32_bf16 v[16:19], v[212:215], v[196:199], v[16:19]
	s_cmp_ge_u32 s33, s49
	v_mfma_f32_16x16x32_bf16 v[12:15], v[220:223], v[196:199], v[12:15]
	s_mov_b32 s2, s33
	v_mfma_f32_16x16x32_bf16 v[8:11], v[212:215], v[204:207], v[8:11]
	v_mfma_f32_16x16x32_bf16 v[4:7], v[220:223], v[204:207], v[4:7]
	v_mfma_f32_16x16x32_bf16 v[48:51], v[216:219], v[184:187], v[48:51]
	v_mfma_f32_16x16x32_bf16 v[44:47], v[224:227], v[184:187], v[44:47]
	v_mfma_f32_16x16x32_bf16 v[32:35], v[216:219], v[192:195], v[32:35]
	v_mfma_f32_16x16x32_bf16 v[28:31], v[224:227], v[192:195], v[28:31]
	v_mfma_f32_16x16x32_bf16 v[16:19], v[216:219], v[200:203], v[16:19]
	v_mfma_f32_16x16x32_bf16 v[12:15], v[224:227], v[200:203], v[12:15]
	v_mfma_f32_16x16x32_bf16 v[8:11], v[216:219], v[208:211], v[8:11]
	v_mfma_f32_16x16x32_bf16 v[4:7], v[224:227], v[208:211], v[4:7]
	s_barrier
; __device__ __forceinline__ unsigned pk2(float lo, float hi) { f32x2_t v = {lo, hi}; bf16x2_t b = __builtin_convertvector(v, bf16x2_t); return __builtin_bit_cast(unsigned, b); }
; #define WAIT_V(n) asm volatile("s_waitcnt vmcnt(" #n ")" ::: "memory")
; #define BAR __builtin_amdgcn_s_barrier()
; #define WAIT_V(n) asm volatile("s_waitcnt vmcnt(" #n ")" ::: "memory")
; #define BAR __builtin_amdgcn_s_barrier()
; __device__ __forceinline__ void gemm_stream(int swave, const GemmJob& J, char* shm, int vb, int G) {
;     ...
;     {
;       bf16_t* C = (bf16_t*)((char*)J.c0 + (size_t)cg * J.strideC);
; #pragma unroll
;       for (int ai = 0; ai < 2; ++ai)
; #pragma unroll
;         for (int m = 0; m < 4; ++m)
; #pragma unroll
;           for (int bj = 0; bj < 2; ++bj) {
;             const f32x4 v0 = acc[ai][bj][m][0], v1 = acc[ai][bj][m][1];
;             uint4 o; o.x = pk2(v0[0], v0[1]); o.y = pk2(v0[2], v0[3]); o.z = pk2(v1[0], v1[1]); o.w = pk2(v1[2], v1[3]);
;             *(uint4*)(C + (size_t)(cbrow + ai * 128 + wr * 64 + m * 16 + fr) * J.ldc + cbcol + bj * 128 + wc * 32 + fq * 8) = o;
;           }
;     }
;     if (!has_next) break;
; #pragma unroll
;     for (int a_ = 0; a_ < 2; ++a_)
; #pragma unroll
;       for (int b_ = 0; b_ < 2; ++b_)
; #pragma unroll
;         for (int m = 0; m < 4; ++m)
; #pragma unroll
;           for (int n = 0; n < 2; ++n) acc[a_][b_][m][n] = (f32x4){0.f, 0.f, 0.f, 0.f};
;     id = nid; cg = ng; cbrow = nbrow; cbcol = nbcol; cA = nA; cA1 = nA1; cB = nB;
;   }
;   WAIT_V(0);
;   if (wr == 0) BAR;
	s_cbranch_scc0 .LBB0_729
	v_add_u32_e32 v164, s5, v1
	s_ashr_i32 s5, s4, 31
	s_lshl_b64 s[2:3], s[4:5], 1
	v_ashrrev_i32_e32 v2, 31, v164
	s_add_u32 s2, s50, s2
	v_cvt_pk_bf16_f32 v128, v128, v129
	v_cvt_pk_bf16_f32 v129, v130, v131
	v_cvt_pk_bf16_f32 v130, v124, v125
	v_mul_lo_u32 v2, v2, s18
	v_mad_u64_u32 v[124:125], s[4:5], v164, s18, 0
	s_addc_u32 s3, s51, s3
	v_add_u32_e32 v125, v125, v2
	v_lshl_add_u64 v[124:125], v[124:125], 1, s[2:3]
	v_mov_b32_e32 v141, v3
	v_lshl_add_u64 v[124:125], v[124:125], 0, v[140:141]
	v_mov_b32_e32 v143, v3
	v_lshl_add_u64 v[124:125], v[124:125], 0, v[142:143]
	s_lshl_b32 s2, s18, 5
	s_mov_b32 s3, 0
	s_mul_i32 s4, s18, 0xa0
	s_mov_b32 s5, 0
	v_cvt_pk_bf16_f32 v112, v112, v113
	v_cvt_pk_bf16_f32 v113, v114, v115
	v_cvt_pk_bf16_f32 v114, v108, v109
	v_cvt_pk_bf16_f32 v115, v110, v111
	global_store_dwordx4 v[124:125], v[112:115], off offset:256
	v_cvt_pk_bf16_f32 v131, v126, v127
	v_cvt_pk_bf16_f32 v96, v96, v97
	v_lshl_add_u64 v[112:113], v[124:125], 0, s[2:3]
	v_cvt_pk_bf16_f32 v97, v98, v99
	v_cvt_pk_bf16_f32 v98, v92, v93
	v_cvt_pk_bf16_f32 v99, v94, v95
	global_store_dwordx4 v[124:125], v[128:131], off
	global_store_dwordx4 v[112:113], v[96:99], off offset:256
	v_cvt_pk_bf16_f32 v108, v120, v121
	v_cvt_pk_bf16_f32 v109, v122, v123
	v_lshl_add_u64 v[96:97], v[112:113], 0, s[2:3]
	v_cvt_pk_bf16_f32 v110, v116, v117
	v_cvt_pk_bf16_f32 v111, v118, v119
	v_cvt_pk_bf16_f32 v80, v80, v81
	v_cvt_pk_bf16_f32 v81, v82, v83
	v_cvt_pk_bf16_f32 v82, v76, v77
	v_cvt_pk_bf16_f32 v83, v78, v79
	global_store_dwordx4 v[112:113], v[108:111], off
	global_store_dwordx4 v[96:97], v[80:83], off offset:256
	v_cvt_pk_bf16_f32 v64, v64, v65
	v_cvt_pk_bf16_f32 v65, v66, v67
	v_lshl_add_u64 v[80:81], v[96:97], 0, s[2:3]
	v_cvt_pk_bf16_f32 v66, v60, v61
	v_lshl_add_u64 v[60:61], v[80:81], 0, s[4:5]
	v_cvt_pk_bf16_f32 v72, v72, v73
	v_cvt_pk_bf16_f32 v73, v74, v75
	v_cvt_pk_bf16_f32 v74, v68, v69
	v_cvt_pk_bf16_f32 v67, v62, v63
	v_cvt_pk_bf16_f32 v92, v104, v105
	v_cvt_pk_bf16_f32 v93, v106, v107
	v_cvt_pk_bf16_f32 v94, v100, v101
	v_cvt_pk_bf16_f32 v95, v102, v103
	v_cvt_pk_bf16_f32 v76, v88, v89
	v_cvt_pk_bf16_f32 v77, v90, v91
	v_cvt_pk_bf16_f32 v78, v84, v85
	v_cvt_pk_bf16_f32 v79, v86, v87
	v_cvt_pk_bf16_f32 v75, v70, v71
	v_cvt_pk_bf16_f32 v48, v48, v49
	v_cvt_pk_bf16_f32 v49, v50, v51
	v_cvt_pk_bf16_f32 v50, v44, v45
	v_cvt_pk_bf16_f32 v51, v46, v47
	global_store_dwordx4 v[96:97], v[92:95], off
	global_store_dwordx4 v[80:81], v[76:79], off
	global_store_dwordx4 v[80:81], v[72:75], off offset:256
	global_store_dwordx4 v[60:61], v[48:51], off offset:256
	v_cvt_pk_bf16_f32 v32, v32, v33
	v_cvt_pk_bf16_f32 v33, v34, v35
	v_lshl_add_u64 v[48:49], v[60:61], 0, s[2:3]
	v_cvt_pk_bf16_f32 v34, v28, v29
	v_cvt_pk_bf16_f32 v35, v30, v31
	global_store_dwordx4 v[60:61], v[64:67], off
	global_store_dwordx4 v[48:49], v[32:35], off offset:256
	v_cvt_pk_bf16_f32 v44, v56, v57
	v_cvt_pk_bf16_f32 v45, v58, v59
	v_lshl_add_u64 v[32:33], v[48:49], 0, s[2:3]
	v_cvt_pk_bf16_f32 v46, v52, v53
	v_cvt_pk_bf16_f32 v47, v54, v55
	v_cvt_pk_bf16_f32 v16, v16, v17
	v_cvt_pk_bf16_f32 v17, v18, v19
	v_cvt_pk_bf16_f32 v18, v12, v13
	v_cvt_pk_bf16_f32 v19, v14, v15
	global_store_dwordx4 v[48:49], v[44:47], off
	global_store_dwordx4 v[32:33], v[16:19], off offset:256
	v_cvt_pk_bf16_f32 v28, v40, v41
	v_cvt_pk_bf16_f32 v29, v42, v43
	v_lshl_add_u64 v[16:17], v[32:33], 0, s[2:3]
	v_cvt_pk_bf16_f32 v30, v36, v37
	v_cvt_pk_bf16_f32 v31, v38, v39
	v_cvt_pk_bf16_f32 v12, v24, v25
	v_cvt_pk_bf16_f32 v13, v26, v27
	v_cvt_pk_bf16_f32 v14, v20, v21
	v_cvt_pk_bf16_f32 v15, v22, v23
	v_cvt_pk_bf16_f32 v8, v8, v9
	v_cvt_pk_bf16_f32 v9, v10, v11
	v_cvt_pk_bf16_f32 v10, v4, v5
	v_cvt_pk_bf16_f32 v11, v6, v7
	s_and_b64 vcc, exec, s[6:7]
	s_mov_b64 s[2:3], s[14:15]
	s_mov_b64 s[16:17], s[12:13]
	s_mov_b64 s[8:9], s[10:11]
	s_mov_b32 s4, s56
	s_mov_b32 s5, s28
	global_store_dwordx4 v[32:33], v[28:31], off
	global_store_dwordx4 v[16:17], v[12:15], off
	global_store_dwordx4 v[16:17], v[8:11], off offset:256
	s_cbranch_vccz .LBB0_726
	s_waitcnt vmcnt(0)
	s_movk_i32 s66, 0x100
	v_cmp_gt_u32_e32 vcc, s66, v135
	s_and_saveexec_b64 s[0:1], vcc
	s_cbranch_execz .LBB0_733
	s_barrier
